# grid barrier: released workgroups poll the cross-XCD generation directly (one hand-off hop less per barrier); plus NA attention loop LDS-read pipelining
# speedup vs baseline: 1.0042x; 1.0042x over previous
; __device__ __forceinline__ unsigned xb_ld(unsigned* p)              { return __hip_atomic_load(p, __ATOMIC_RELAXED, __HIP_MEMORY_SCOPE_AGENT); }
; __device__ __forceinline__ unsigned xb_add(unsigned* p, unsigned v) { return __hip_atomic_fetch_add(p, v, __ATOMIC_RELAXED, __HIP_MEMORY_SCOPE_AGENT); }
; #define XB_SPIN(cond, bar) do { unsigned _sp = 0; while (cond) { __builtin_amdgcn_s_sleep(1); \
;     if ((++_sp & 255u) == 0u) { if (xb_ld(&(bar)[XB_TMO])) break; if (_sp > XB_SPIN_CAP) { atomicAdd(&(bar)[XB_TMO], 1u); break; } } } } while (0)
; __device__ __forceinline__ void xcd_barrier(const XcdBarrier& b) {
;     ...
;         const unsigned old = xb_add(&bar[XB_XSUB(b.x)], 1u);
;         const unsigned gen = old / nloc;
;         if (old + 1u == (gen + 1u) * nloc) {
;     ...
;             XB_SPIN(xb_ld(&bar[XB_XGEN(b.x)]) == gen, bar);
.LBB0_289:
	s_or_b64 exec, exec, s[8:9]
	v_cvt_f32_u32_e32 v4, v2
	s_waitcnt vmcnt(0)
	v_readfirstlane_b32 s6, v3
	v_sub_u32_e32 v3, 0, v2
	v_rcp_iflag_f32_e32 v4, v4
	v_add_u32_e32 v5, s6, v1
	v_mul_f32_e32 v4, 0x4f7ffffe, v4
	v_cvt_u32_f32_e32 v4, v4
	v_mul_lo_u32 v1, v3, v4
	v_mul_hi_u32 v1, v4, v1
	v_add_u32_e32 v1, v4, v1
	v_mul_hi_u32 v1, v5, v1
	v_mul_lo_u32 v3, v1, v2
	v_sub_u32_e32 v3, v5, v3
	v_add_u32_e32 v4, 1, v1
	v_cmp_ge_u32_e32 vcc, v3, v2
	s_nop 1
	v_cndmask_b32_e32 v1, v1, v4, vcc
	v_sub_u32_e32 v4, v3, v2
	v_cndmask_b32_e32 v3, v3, v4, vcc
	v_add_u32_e32 v4, 1, v1
	v_cmp_ge_u32_e32 vcc, v3, v2
	v_add_u32_e32 v3, 1, v5
	s_nop 0
	v_cndmask_b32_e32 v1, v1, v4, vcc
	v_mul_lo_u32 v4, v2, v1
	v_add_u32_e32 v2, v4, v2
	v_cmp_ne_u32_e32 vcc, v3, v2
	s_and_saveexec_b64 s[6:7], vcc
	s_xor_b64 s[6:7], exec, s[6:7]
	s_cbranch_execz .LBB0_303
	s_waitcnt lgkmcnt(0)
	v_mov_b32_e32 v0, 0x7500
	global_load_dword v0, v0, s[22:23] sc1
	s_add_u32 s12, s22, 0x7500
	s_addc_u32 s13, s23, 0
	s_waitcnt vmcnt(0)
	v_cmp_eq_u32_e32 vcc, v0, v1
	s_and_saveexec_b64 s[8:9], vcc
	s_cbranch_execz .LBB0_302
	s_add_u32 s10, s22, 0x4200
	s_addc_u32 s11, s23, 0
	s_mov_b32 s28, 1
	s_mov_b64 s[14:15], 0
	v_mov_b32_e32 v0, 0
	s_branch .LBB0_293

; __device__ __forceinline__ unsigned xb_ld(unsigned* p)              { return __hip_atomic_load(p, __ATOMIC_RELAXED, __HIP_MEMORY_SCOPE_AGENT); }
; #define XB_SPIN(cond, bar) do { unsigned _sp = 0; while (cond) { __builtin_amdgcn_s_sleep(1); \
;     if ((++_sp & 255u) == 0u) { if (xb_ld(&(bar)[XB_TMO])) break; if (_sp > XB_SPIN_CAP) { atomicAdd(&(bar)[XB_TMO], 1u); break; } } } } while (0)
; __device__ __forceinline__ void xcd_barrier(const XcdBarrier& b) {
;     ...
;             XB_SPIN(xb_ld(&bar[XB_XGEN(b.x)]) == gen, bar);
.LBB0_366:
	s_or_b64 exec, exec, s[2:3]
	v_cvt_f32_u32_e32 v5, v3
	s_waitcnt vmcnt(0)
	v_readfirstlane_b32 s2, v4
	v_sub_u32_e32 v4, 0, v3
	v_rcp_iflag_f32_e32 v5, v5
	v_add_u32_e32 v6, s2, v0
	v_mul_f32_e32 v5, 0x4f7ffffe, v5
	v_cvt_u32_f32_e32 v5, v5
	v_mul_lo_u32 v0, v4, v5
	v_mul_hi_u32 v0, v5, v0
	v_add_u32_e32 v0, v5, v0
	v_mul_hi_u32 v0, v6, v0
	v_mul_lo_u32 v4, v0, v3
	v_sub_u32_e32 v4, v6, v4
	v_add_u32_e32 v5, 1, v0
	v_cmp_ge_u32_e32 vcc, v4, v3
	s_nop 1
	v_cndmask_b32_e32 v0, v0, v5, vcc
	v_sub_u32_e32 v5, v4, v3
	v_cndmask_b32_e32 v4, v4, v5, vcc
	v_add_u32_e32 v5, 1, v0
	v_cmp_ge_u32_e32 vcc, v4, v3
	v_add_u32_e32 v4, 1, v6
	s_nop 0
	v_cndmask_b32_e32 v0, v0, v5, vcc
	v_mul_lo_u32 v5, v3, v0
	v_add_u32_e32 v3, v5, v3
	v_cmp_ne_u32_e32 vcc, v4, v3
	s_and_saveexec_b64 s[2:3], vcc
	s_xor_b64 s[2:3], exec, s[2:3]
	s_cbranch_execz .LBB0_380
	v_readlane_b32 s6, v252, 0
	v_readlane_b32 s7, v252, 1
	s_waitcnt lgkmcnt(0)
	s_nop 3
	global_load_dword v2, v1, s[6:7] sc1
	s_waitcnt vmcnt(0)
	v_cmp_eq_u32_e32 vcc, v2, v0
	s_and_saveexec_b64 s[14:15], vcc
	s_cbranch_execz .LBB0_379
	s_mov_b32 s26, 1
	s_mov_b64 s[16:17], 0
	s_branch .LBB0_370

; __device__ __forceinline__ unsigned xb_ld(unsigned* p)              { return __hip_atomic_load(p, __ATOMIC_RELAXED, __HIP_MEMORY_SCOPE_AGENT); }
; #define XB_SPIN(cond, bar) do { unsigned _sp = 0; while (cond) { __builtin_amdgcn_s_sleep(1); \
;     if ((++_sp & 255u) == 0u) { if (xb_ld(&(bar)[XB_TMO])) break; if (_sp > XB_SPIN_CAP) { atomicAdd(&(bar)[XB_TMO], 1u); break; } } } } while (0)
; __device__ __forceinline__ void xcd_barrier(const XcdBarrier& b) {
;     ...
;             XB_SPIN(xb_ld(&bar[XB_XGEN(b.x)]) == gen, bar);
.LBB0_1816:
	s_or_b64 exec, exec, s[2:3]
	v_cvt_f32_u32_e32 v5, v3
	s_waitcnt vmcnt(0)
	v_readfirstlane_b32 s2, v4
	v_sub_u32_e32 v4, 0, v3
	v_rcp_iflag_f32_e32 v5, v5
	v_add_u32_e32 v6, s2, v0
	v_mul_f32_e32 v5, 0x4f7ffffe, v5
	v_cvt_u32_f32_e32 v5, v5
	v_mul_lo_u32 v0, v4, v5
	v_mul_hi_u32 v0, v5, v0
	v_add_u32_e32 v0, v5, v0
	v_mul_hi_u32 v0, v6, v0
	v_mul_lo_u32 v4, v0, v3
	v_sub_u32_e32 v4, v6, v4
	v_add_u32_e32 v5, 1, v0
	v_cmp_ge_u32_e32 vcc, v4, v3
	s_nop 1
	v_cndmask_b32_e32 v0, v0, v5, vcc
	v_sub_u32_e32 v5, v4, v3
	v_cndmask_b32_e32 v4, v4, v5, vcc
	v_add_u32_e32 v5, 1, v0
	v_cmp_ge_u32_e32 vcc, v4, v3
	v_add_u32_e32 v4, 1, v6
	s_nop 0
	v_cndmask_b32_e32 v0, v0, v5, vcc
	v_mul_lo_u32 v5, v3, v0
	v_add_u32_e32 v3, v5, v3
	v_cmp_ne_u32_e32 vcc, v4, v3
	s_and_saveexec_b64 s[2:3], vcc
	s_xor_b64 s[2:3], exec, s[2:3]
	s_cbranch_execz .LBB0_1830
	v_readlane_b32 s4, v252, 0
	v_readlane_b32 s5, v252, 1
	s_waitcnt lgkmcnt(0)
	s_nop 3
	global_load_dword v2, v1, s[4:5] sc1
	s_waitcnt vmcnt(0)
	v_cmp_eq_u32_e32 vcc, v2, v0
	s_and_saveexec_b64 s[14:15], vcc
	s_cbranch_execz .LBB0_1829
	s_mov_b32 s4, 1
	s_mov_b64 s[16:17], 0
	s_branch .LBB0_1820

; __device__ __forceinline__ unsigned xb_ld(unsigned* p)              { return __hip_atomic_load(p, __ATOMIC_RELAXED, __HIP_MEMORY_SCOPE_AGENT); }
; #define XB_SPIN(cond, bar) do { unsigned _sp = 0; while (cond) { __builtin_amdgcn_s_sleep(1); \
;     if ((++_sp & 255u) == 0u) { if (xb_ld(&(bar)[XB_TMO])) break; if (_sp > XB_SPIN_CAP) { atomicAdd(&(bar)[XB_TMO], 1u); break; } } } } while (0)
; __device__ __forceinline__ void xcd_barrier(const XcdBarrier& b) {
;     ...
;             XB_SPIN(xb_ld(&bar[XB_XGEN(b.x)]) == gen, bar);
.LBB0_2125:
	s_or_b64 exec, exec, s[2:3]
	v_cvt_f32_u32_e32 v5, v3
	s_waitcnt vmcnt(0)
	v_readfirstlane_b32 s2, v4
	v_sub_u32_e32 v4, 0, v3
	v_rcp_iflag_f32_e32 v5, v5
	v_add_u32_e32 v6, s2, v0
	v_mul_f32_e32 v5, 0x4f7ffffe, v5
	v_cvt_u32_f32_e32 v5, v5
	v_mul_lo_u32 v0, v4, v5
	v_mul_hi_u32 v0, v5, v0
	v_add_u32_e32 v0, v5, v0
	v_mul_hi_u32 v0, v6, v0
	v_mul_lo_u32 v4, v0, v3
	v_sub_u32_e32 v4, v6, v4
	v_add_u32_e32 v5, 1, v0
	v_cmp_ge_u32_e32 vcc, v4, v3
	s_nop 1
	v_cndmask_b32_e32 v0, v0, v5, vcc
	v_sub_u32_e32 v5, v4, v3
	v_cndmask_b32_e32 v4, v4, v5, vcc
	v_add_u32_e32 v5, 1, v0
	v_cmp_ge_u32_e32 vcc, v4, v3
	v_add_u32_e32 v4, 1, v6
	s_nop 0
	v_cndmask_b32_e32 v0, v0, v5, vcc
	v_mul_lo_u32 v5, v3, v0
	v_add_u32_e32 v3, v5, v3
	v_cmp_ne_u32_e32 vcc, v4, v3
	s_and_saveexec_b64 s[2:3], vcc
	s_xor_b64 s[2:3], exec, s[2:3]
	s_cbranch_execz .LBB0_2139
	v_readlane_b32 s4, v252, 0
	v_readlane_b32 s5, v252, 1
	s_waitcnt lgkmcnt(0)
	s_nop 3
	global_load_dword v2, v1, s[4:5] sc1
	s_waitcnt vmcnt(0)
	v_cmp_eq_u32_e32 vcc, v2, v0
	s_and_saveexec_b64 s[8:9], vcc
	s_cbranch_execz .LBB0_2138
	s_mov_b32 s4, 1
	s_mov_b64 s[10:11], 0
	s_branch .LBB0_2129

; __device__ __forceinline__ unsigned xb_ld(unsigned* p)              { return __hip_atomic_load(p, __ATOMIC_RELAXED, __HIP_MEMORY_SCOPE_AGENT); }
; #define XB_SPIN(cond, bar) do { unsigned _sp = 0; while (cond) { __builtin_amdgcn_s_sleep(1); \
;     if ((++_sp & 255u) == 0u) { if (xb_ld(&(bar)[XB_TMO])) break; if (_sp > XB_SPIN_CAP) { atomicAdd(&(bar)[XB_TMO], 1u); break; } } } } while (0)
; __device__ __forceinline__ void xcd_barrier(const XcdBarrier& b) {
;     ...
;             XB_SPIN(xb_ld(&bar[XB_XGEN(b.x)]) == gen, bar);
.LBB0_2187:
	s_or_b64 exec, exec, s[2:3]
	v_cvt_f32_u32_e32 v5, v3
	s_waitcnt vmcnt(0)
	v_readfirstlane_b32 s2, v4
	v_sub_u32_e32 v4, 0, v3
	v_rcp_iflag_f32_e32 v5, v5
	v_add_u32_e32 v6, s2, v0
	v_mul_f32_e32 v5, 0x4f7ffffe, v5
	v_cvt_u32_f32_e32 v5, v5
	v_mul_lo_u32 v0, v4, v5
	v_mul_hi_u32 v0, v5, v0
	v_add_u32_e32 v0, v5, v0
	v_mul_hi_u32 v0, v6, v0
	v_mul_lo_u32 v4, v0, v3
	v_sub_u32_e32 v4, v6, v4
	v_add_u32_e32 v5, 1, v0
	v_cmp_ge_u32_e32 vcc, v4, v3
	s_nop 1
	v_cndmask_b32_e32 v0, v0, v5, vcc
	v_sub_u32_e32 v5, v4, v3
	v_cndmask_b32_e32 v4, v4, v5, vcc
	v_add_u32_e32 v5, 1, v0
	v_cmp_ge_u32_e32 vcc, v4, v3
	v_add_u32_e32 v4, 1, v6
	s_nop 0
	v_cndmask_b32_e32 v0, v0, v5, vcc
	v_mul_lo_u32 v5, v3, v0
	v_add_u32_e32 v3, v5, v3
	v_cmp_ne_u32_e32 vcc, v4, v3
	s_and_saveexec_b64 s[2:3], vcc
	s_xor_b64 s[2:3], exec, s[2:3]
	s_cbranch_execz .LBB0_2201
	v_readlane_b32 s4, v252, 0
	v_readlane_b32 s5, v252, 1
	s_waitcnt lgkmcnt(0)
	s_nop 3
	global_load_dword v2, v1, s[4:5] sc1
	s_waitcnt vmcnt(0)
	v_cmp_eq_u32_e32 vcc, v2, v0
	s_and_saveexec_b64 s[6:7], vcc
	s_cbranch_execz .LBB0_2200
	s_mov_b32 s4, 1
	s_mov_b64 s[8:9], 0
	s_branch .LBB0_2191

; __device__ __forceinline__ unsigned xb_ld(unsigned* p)              { return __hip_atomic_load(p, __ATOMIC_RELAXED, __HIP_MEMORY_SCOPE_AGENT); }
; #define XB_SPIN(cond, bar) do { unsigned _sp = 0; while (cond) { __builtin_amdgcn_s_sleep(1); \
;     if ((++_sp & 255u) == 0u) { if (xb_ld(&(bar)[XB_TMO])) break; if (_sp > XB_SPIN_CAP) { atomicAdd(&(bar)[XB_TMO], 1u); break; } } } } while (0)
; __device__ __forceinline__ void xcd_barrier(const XcdBarrier& b) {
;     ...
;             XB_SPIN(xb_ld(&bar[XB_XGEN(b.x)]) == gen, bar);
.LBB0_2457:
	s_or_b64 exec, exec, s[2:3]
	v_cvt_f32_u32_e32 v5, v3
	s_waitcnt vmcnt(0)
	v_readfirstlane_b32 s2, v4
	v_sub_u32_e32 v4, 0, v3
	v_rcp_iflag_f32_e32 v5, v5
	v_add_u32_e32 v6, s2, v0
	v_mul_f32_e32 v5, 0x4f7ffffe, v5
	v_cvt_u32_f32_e32 v5, v5
	v_mul_lo_u32 v0, v4, v5
	v_mul_hi_u32 v0, v5, v0
	v_add_u32_e32 v0, v5, v0
	v_mul_hi_u32 v0, v6, v0
	v_mul_lo_u32 v4, v0, v3
	v_sub_u32_e32 v4, v6, v4
	v_add_u32_e32 v5, 1, v0
	v_cmp_ge_u32_e32 vcc, v4, v3
	s_nop 1
	v_cndmask_b32_e32 v0, v0, v5, vcc
	v_sub_u32_e32 v5, v4, v3
	v_cndmask_b32_e32 v4, v4, v5, vcc
	v_add_u32_e32 v5, 1, v0
	v_cmp_ge_u32_e32 vcc, v4, v3
	v_add_u32_e32 v4, 1, v6
	s_nop 0
	v_cndmask_b32_e32 v0, v0, v5, vcc
	v_mul_lo_u32 v5, v3, v0
	v_add_u32_e32 v3, v5, v3
	v_cmp_ne_u32_e32 vcc, v4, v3
	s_and_saveexec_b64 s[2:3], vcc
	s_xor_b64 s[2:3], exec, s[2:3]
	s_cbranch_execz .LBB0_2471
	v_readlane_b32 s6, v252, 0
	v_readlane_b32 s7, v252, 1
	s_waitcnt lgkmcnt(0)
	s_nop 3
	global_load_dword v2, v1, s[6:7] sc1
	s_waitcnt vmcnt(0)
	v_cmp_eq_u32_e32 vcc, v2, v0
	s_and_saveexec_b64 s[6:7], vcc
	s_cbranch_execz .LBB0_2470
	s_mov_b32 s4, 1
	s_mov_b64 s[8:9], 0
	s_branch .LBB0_2461
